# plus: residual-norm phase issues all eight y loads together instead of four serialized round trips
# speedup vs baseline: 1.0097x; 1.0097x over previous
.LBB0_1105:
	s_ashr_i32 s7, s6, 31
	s_lshl_b64 s[40:41], s[6:7], 13
	v_lshl_add_u64 v[2:3], v[36:37], 0, s[40:41]
	global_load_dwordx4 v[10:13], v[2:3], off
	global_load_dwordx4 v[18:21], v[2:3], off offset:1024
	global_load_dwordx4 v[22:25], v[2:3], off offset:2048
	global_load_dwordx4 v[30:33], v[2:3], off offset:3072
	v_add_co_u32_e32 v2, vcc, 0x1000, v2
	s_lshl_b64 s[10:11], s[6:7], 12
	s_nop 0
	v_addc_co_u32_e32 v3, vcc, 0, v3, vcc
	v_lshl_add_u64 v[76:77], v[38:39], 0, s[10:11]
	global_load_dwordx4 v[26:29], v[2:3], off
	global_load_dwordx4 v[14:17], v[2:3], off offset:1024
	global_load_dwordx4 v[6:9], v[2:3], off offset:2048
	s_nop 0
	global_load_dwordx4 v[2:5], v[2:3], off offset:3072
	s_mov_b32 s2, 0x800000
	global_load_dwordx2 v[116:117], v[76:77], off
	global_load_dwordx2 v[118:119], v[76:77], off offset:512
	global_load_dwordx2 v[120:121], v[76:77], off offset:1024
	global_load_dwordx2 v[122:123], v[76:77], off offset:1536
	global_load_dwordx2 v[78:79], v[76:77], off offset:2048
	global_load_dwordx2 v[80:81], v[76:77], off offset:2560
	global_load_dwordx2 v[108:109], v[76:77], off offset:3072
	global_load_dwordx2 v[82:83], v[76:77], off offset:3584
	s_ashr_i32 s24, s6, 12
	s_mul_i32 s58, s24, 0x6000
	s_mul_hi_i32 s7, s24, 0x6000
	v_lshlrev_b32_e32 v43, 2, v42
	v_lshlrev_b32_e32 v45, 2, v44
	v_lshlrev_b32_e32 v47, 2, v46
	v_lshlrev_b32_e32 v49, 2, v48
	v_lshlrev_b32_e32 v53, 2, v52
	v_lshlrev_b32_e32 v57, 2, v56
	v_lshlrev_b32_e32 v61, 2, v60
	s_waitcnt vmcnt(7)
	v_lshlrev_b32_e32 v104, 16, v116
	v_and_b32_e32 v105, 0xffff0000, v116
	v_lshlrev_b32_e32 v106, 16, v117
	v_and_b32_e32 v107, 0xffff0000, v117
	v_mul_f32_e32 v0, v105, v105
	v_fmac_f32_e32 v0, v104, v104
	v_fmac_f32_e32 v0, v106, v106
	v_fmac_f32_e32 v0, v107, v107
	s_waitcnt vmcnt(6)
	v_lshlrev_b32_e32 v100, 16, v118
	v_and_b32_e32 v101, 0xffff0000, v118
	v_lshlrev_b32_e32 v102, 16, v119
	v_and_b32_e32 v103, 0xffff0000, v119
	v_mul_f32_e32 v35, v101, v101
	v_fmac_f32_e32 v35, v100, v100
	v_fmac_f32_e32 v35, v102, v102
	v_fmac_f32_e32 v35, v103, v103
	v_add_f32_e32 v0, v0, v35
	s_waitcnt vmcnt(5)
	v_lshlrev_b32_e32 v96, 16, v120
	v_and_b32_e32 v97, 0xffff0000, v120
	v_lshlrev_b32_e32 v98, 16, v121
	v_and_b32_e32 v99, 0xffff0000, v121
	v_mul_f32_e32 v35, v97, v97
	v_fmac_f32_e32 v35, v96, v96
	v_fmac_f32_e32 v35, v98, v98
	v_fmac_f32_e32 v35, v99, v99
	v_add_f32_e32 v0, v0, v35
	s_waitcnt vmcnt(4)
	v_lshlrev_b32_e32 v92, 16, v122
	v_and_b32_e32 v93, 0xffff0000, v122
	v_lshlrev_b32_e32 v94, 16, v123
	v_and_b32_e32 v95, 0xffff0000, v123
	v_mul_f32_e32 v35, v93, v93
	v_fmac_f32_e32 v35, v92, v92
	v_fmac_f32_e32 v35, v94, v94
	v_fmac_f32_e32 v35, v95, v95
	v_add_f32_e32 v0, v0, v35
	s_waitcnt vmcnt(3)
	v_and_b32_e32 v86, 0xffff0000, v78
	s_waitcnt vmcnt(2)
	v_and_b32_e32 v87, 0xffff0000, v80
	v_lshlrev_b32_e32 v85, 16, v80
	v_lshlrev_b32_e32 v84, 16, v78
	v_lshlrev_b32_e32 v88, 16, v79
	v_and_b32_e32 v90, 0xffff0000, v79
	v_pk_mul_f32 v[78:79], v[86:87], v[86:87]
	v_lshlrev_b32_e32 v89, 16, v81
	v_pk_fma_f32 v[78:79], v[84:85], v[84:85], v[78:79]
	v_and_b32_e32 v91, 0xffff0000, v81
	v_pk_fma_f32 v[78:79], v[88:89], v[88:89], v[78:79]
	s_waitcnt vmcnt(0)
	v_lshlrev_b32_e32 v77, 16, v82
	v_pk_fma_f32 v[78:79], v[90:91], v[90:91], v[78:79]
	v_lshlrev_b32_e32 v76, 16, v108
	v_add_f32_e32 v0, v0, v78
	v_add_f32_e32 v0, v0, v79
	v_and_b32_e32 v79, 0xffff0000, v82
	v_and_b32_e32 v78, 0xffff0000, v108
	v_lshlrev_b32_e32 v80, 16, v109
	v_and_b32_e32 v82, 0xffff0000, v109
	v_pk_mul_f32 v[108:109], v[78:79], v[78:79]
	v_lshlrev_b32_e32 v81, 16, v83
	v_pk_fma_f32 v[108:109], v[76:77], v[76:77], v[108:109]
	v_and_b32_e32 v83, 0xffff0000, v83
	v_pk_fma_f32 v[108:109], v[80:81], v[80:81], v[108:109]
	s_nop 0
	v_pk_fma_f32 v[108:109], v[82:83], v[82:83], v[108:109]
	s_nop 0
	v_add_f32_e32 v0, v0, v108
	v_add_f32_e32 v0, v0, v109
	s_nop 1
	v_add_f32_dpp v0, v0, v0 quad_perm:[1,0,3,2] row_mask:0xf bank_mask:0xf bound_ctrl:1
	s_nop 1
	v_add_f32_dpp v0, v0, v0 quad_perm:[2,3,0,1] row_mask:0xf bank_mask:0xf bound_ctrl:1
	s_nop 1
	v_add_f32_dpp v0, v0, v0 row_ror:4 row_mask:0xf bank_mask:0xf bound_ctrl:1
	s_nop 1
	v_add_f32_dpp v0, v0, v0 row_ror:8 row_mask:0xf bank_mask:0xf bound_ctrl:1
	ds_bpermute_b32 v35, v207, v0
	s_waitcnt lgkmcnt(0)
	v_add_f32_e32 v0, v0, v35
	ds_bpermute_b32 v35, v209, v0
	s_waitcnt lgkmcnt(0)
	v_add_f32_e32 v0, v0, v35
	v_fmamk_f32 v0, v0, 0x3a000000, v166
	v_cmp_gt_f32_e32 vcc, s2, v0
	v_mul_f32_e32 v35, 0x4b800000, v0
	s_add_u32 s2, s54, s58
	v_cndmask_b32_e32 v0, v0, v35, vcc
	v_rsq_f32_e32 v0, v0
	s_addc_u32 s17, s55, s7
	s_add_u32 s42, s2, 0x4000
	s_addc_u32 s43, s17, 0
	v_mul_f32_e32 v35, 0x45800000, v0
	v_cndmask_b32_e32 v0, v0, v35, vcc
	v_lshlrev_b32_e32 v35, 2, v34
	global_load_dwordx4 v[108:111], v35, s[42:43]
	global_load_dwordx4 v[112:115], v[40:41], off
	v_pk_mul_f32 v[106:107], v[106:107], v[0:1] op_sel_hi:[1,0]
	v_pk_mul_f32 v[104:105], v[104:105], v[0:1] op_sel_hi:[1,0]
	s_add_u32 s40, s84, s40
	s_addc_u32 s41, s85, s41
	v_pk_mul_f32 v[100:101], v[100:101], v[0:1] op_sel_hi:[1,0]
	v_pk_mul_f32 v[102:103], v[102:103], v[0:1] op_sel_hi:[1,0]
	v_pk_mul_f32 v[96:97], v[96:97], v[0:1] op_sel_hi:[1,0]
	v_pk_mul_f32 v[98:99], v[98:99], v[0:1] op_sel_hi:[1,0]
	v_pk_mul_f32 v[92:93], v[92:93], v[0:1] op_sel_hi:[1,0]
	v_pk_mul_f32 v[94:95], v[94:95], v[0:1] op_sel_hi:[1,0]
	s_andn2_b64 vcc, exec, s[0:1]
	s_waitcnt vmcnt(1)
	v_pk_mul_f32 v[104:105], v[108:109], v[104:105]
	v_pk_mul_f32 v[106:107], v[110:111], v[106:107]
	s_waitcnt vmcnt(0)
	v_pk_fma_f32 v[10:11], v[112:113], v[104:105], v[10:11]
	v_pk_fma_f32 v[12:13], v[114:115], v[106:107], v[12:13]
	global_store_dwordx4 v35, v[10:13], s[40:41]
	global_load_dwordx4 v[104:107], v43, s[42:43]
	global_load_dwordx4 v[108:111], v[40:41], off offset:1024
	s_waitcnt vmcnt(1)
	v_pk_mul_f32 v[102:103], v[106:107], v[102:103]
	v_pk_mul_f32 v[100:101], v[104:105], v[100:101]
	s_waitcnt vmcnt(0)
	v_pk_fma_f32 v[20:21], v[110:111], v[102:103], v[20:21]
	v_pk_fma_f32 v[18:19], v[108:109], v[100:101], v[18:19]
	global_store_dwordx4 v35, v[18:21], s[40:41] offset:1024
	global_load_dwordx4 v[100:103], v45, s[42:43]
	global_load_dwordx4 v[104:107], v[40:41], off offset:2048
	s_waitcnt vmcnt(1)
	v_pk_mul_f32 v[98:99], v[102:103], v[98:99]
	v_pk_mul_f32 v[96:97], v[100:101], v[96:97]
	s_waitcnt vmcnt(0)
	v_pk_fma_f32 v[24:25], v[106:107], v[98:99], v[24:25]
	v_pk_fma_f32 v[22:23], v[104:105], v[96:97], v[22:23]
	global_store_dwordx4 v35, v[22:25], s[40:41] offset:2048
	global_load_dwordx4 v[96:99], v47, s[42:43]
	global_load_dwordx4 v[100:103], v[40:41], off offset:3072
	s_waitcnt vmcnt(1)
	v_pk_mul_f32 v[94:95], v[98:99], v[94:95]
	v_pk_mul_f32 v[92:93], v[96:97], v[92:93]
	s_waitcnt vmcnt(0)
	v_pk_fma_f32 v[32:33], v[102:103], v[94:95], v[32:33]
	v_pk_fma_f32 v[30:31], v[100:101], v[92:93], v[30:31]
	global_store_dwordx4 v35, v[30:33], s[40:41] offset:3072
	global_load_dwordx4 v[92:95], v49, s[42:43]
	global_load_dwordx4 v[96:99], v[50:51], off
	v_mov_b32_e32 v100, v84
	v_mov_b32_e32 v101, v86
	v_mov_b32_e32 v102, v88
	v_mov_b32_e32 v103, v90
	v_pk_mul_f32 v[100:101], v[100:101], v[0:1] op_sel_hi:[1,0]
	v_pk_mul_f32 v[102:103], v[102:103], v[0:1] op_sel_hi:[1,0]
	v_mov_b32_e32 v86, v85
	v_mov_b32_e32 v90, v89
	v_pk_mul_f32 v[84:85], v[86:87], v[0:1] op_sel_hi:[1,0]
	v_pk_mul_f32 v[86:87], v[90:91], v[0:1] op_sel_hi:[1,0]
	s_waitcnt vmcnt(1)
	v_pk_mul_f32 v[94:95], v[94:95], v[102:103]
	v_pk_mul_f32 v[92:93], v[92:93], v[100:101]
	s_waitcnt vmcnt(0)
	v_pk_fma_f32 v[28:29], v[98:99], v[94:95], v[28:29]
	v_pk_fma_f32 v[26:27], v[96:97], v[92:93], v[26:27]
	global_store_dwordx4 v49, v[26:29], s[40:41]
	global_load_dwordx4 v[92:95], v53, s[42:43]
	global_load_dwordx4 v[96:99], v[54:55], off
	s_waitcnt vmcnt(1)
	v_pk_mul_f32 v[86:87], v[94:95], v[86:87]
	v_pk_mul_f32 v[84:85], v[92:93], v[84:85]
	s_waitcnt vmcnt(0)
	v_pk_fma_f32 v[16:17], v[98:99], v[86:87], v[16:17]
	v_pk_fma_f32 v[14:15], v[96:97], v[84:85], v[14:15]
	global_store_dwordx4 v53, v[14:17], s[40:41]
	global_load_dwordx4 v[84:87], v57, s[42:43]
	global_load_dwordx4 v[88:91], v[58:59], off
	v_mov_b32_e32 v92, v76
	v_mov_b32_e32 v93, v78
	v_mov_b32_e32 v94, v80
	v_mov_b32_e32 v95, v82
	v_pk_mul_f32 v[92:93], v[92:93], v[0:1] op_sel_hi:[1,0]
	v_pk_mul_f32 v[94:95], v[94:95], v[0:1] op_sel_hi:[1,0]
	v_mov_b32_e32 v78, v77
	v_mov_b32_e32 v82, v81
	v_pk_mul_f32 v[76:77], v[78:79], v[0:1] op_sel_hi:[1,0]
	v_pk_mul_f32 v[78:79], v[82:83], v[0:1] op_sel_hi:[1,0]
	s_waitcnt vmcnt(1)
	v_pk_mul_f32 v[86:87], v[94:95], v[86:87]
	v_pk_mul_f32 v[84:85], v[92:93], v[84:85]
	s_waitcnt vmcnt(0)
	v_pk_fma_f32 v[8:9], v[90:91], v[86:87], v[8:9]
	v_pk_fma_f32 v[6:7], v[88:89], v[84:85], v[6:7]
	global_store_dwordx4 v57, v[6:9], s[40:41]
	global_load_dwordx4 v[84:87], v61, s[42:43]
	global_load_dwordx4 v[88:91], v[62:63], off
	s_waitcnt vmcnt(1)
	v_pk_mul_f32 v[78:79], v[78:79], v[86:87]
	v_pk_mul_f32 v[76:77], v[76:77], v[84:85]
	s_waitcnt vmcnt(0)
	v_pk_fma_f32 v[4:5], v[90:91], v[78:79], v[4:5]
	v_pk_fma_f32 v[2:3], v[88:89], v[76:77], v[2:3]
	global_store_dwordx4 v61, v[2:5], s[40:41]
	s_cbranch_vccnz .LBB0_1104
	v_mul_f32_e32 v0, v11, v11
	v_mul_f32_e32 v76, v19, v19
	v_fmac_f32_e32 v0, v10, v10
	v_fmac_f32_e32 v76, v18, v18
	v_fmac_f32_e32 v0, v12, v12
	v_fmac_f32_e32 v76, v20, v20
	v_fmac_f32_e32 v0, v13, v13
	v_fmac_f32_e32 v76, v21, v21
	v_add_f32_e32 v0, v0, v76
	v_mul_f32_e32 v76, v23, v23
	v_fmac_f32_e32 v76, v22, v22
	v_fmac_f32_e32 v76, v24, v24
	v_fmac_f32_e32 v76, v25, v25
	v_add_f32_e32 v0, v76, v0
	v_mul_f32_e32 v76, v31, v31
	v_fmac_f32_e32 v76, v30, v30
	v_fmac_f32_e32 v76, v32, v32
	v_fmac_f32_e32 v76, v33, v33
	v_mov_b32_e32 v78, v15
	v_mov_b32_e32 v79, v27
	v_add_f32_e32 v0, v76, v0
	v_mov_b32_e32 v76, v14
	v_mov_b32_e32 v77, v26
	v_pk_mul_f32 v[78:79], v[78:79], v[78:79]
	s_mov_b32 s2, 0x800000
	v_pk_fma_f32 v[76:77], v[76:77], v[76:77], v[78:79]
	v_mov_b32_e32 v78, v16
	v_mov_b32_e32 v79, v28
	v_pk_fma_f32 v[76:77], v[78:79], v[78:79], v[76:77]
	v_mov_b32_e32 v78, v17
	v_mov_b32_e32 v79, v29
	v_pk_fma_f32 v[76:77], v[78:79], v[78:79], v[76:77]
	v_mov_b32_e32 v78, v3
	v_add_f32_e32 v0, v77, v0
	v_mov_b32_e32 v79, v7
	v_add_f32_e32 v0, v76, v0
	v_mov_b32_e32 v76, v2
	v_mov_b32_e32 v77, v6
	v_pk_mul_f32 v[78:79], v[78:79], v[78:79]
	s_add_u32 s42, s62, s58
	v_pk_fma_f32 v[76:77], v[76:77], v[76:77], v[78:79]
	v_mov_b32_e32 v78, v4
	v_mov_b32_e32 v79, v8
	v_pk_fma_f32 v[76:77], v[78:79], v[78:79], v[76:77]
	v_mov_b32_e32 v78, v5
	v_mov_b32_e32 v79, v9
	v_pk_fma_f32 v[76:77], v[78:79], v[78:79], v[76:77]
	s_addc_u32 s43, s63, s7
	v_add_f32_e32 v0, v77, v0
	v_add_f32_e32 v0, v76, v0
	s_add_u32 s40, s42, 0x2000
	s_addc_u32 s41, s43, 0
	v_add_f32_dpp v0, v0, v0 quad_perm:[1,0,3,2] row_mask:0xf bank_mask:0xf bound_ctrl:1
	s_nop 1
	v_add_f32_dpp v0, v0, v0 quad_perm:[2,3,0,1] row_mask:0xf bank_mask:0xf bound_ctrl:1
	s_nop 1
	v_add_f32_dpp v0, v0, v0 row_ror:4 row_mask:0xf bank_mask:0xf bound_ctrl:1
	s_nop 1
	v_add_f32_dpp v0, v0, v0 row_ror:8 row_mask:0xf bank_mask:0xf bound_ctrl:1
	ds_bpermute_b32 v76, v207, v0
	s_waitcnt lgkmcnt(0)
	v_add_f32_e32 v0, v0, v76
	ds_bpermute_b32 v76, v209, v0
	s_waitcnt lgkmcnt(0)
	v_add_f32_e32 v0, v0, v76
	v_fmamk_f32 v0, v0, 0x3a000000, v166
	v_cmp_gt_f32_e32 vcc, s2, v0
	v_mul_f32_e32 v76, 0x4b800000, v0
	s_nop 0
	v_cndmask_b32_e32 v0, v0, v76, vcc
	v_rsq_f32_e32 v0, v0
	s_nop 0
	v_mul_f32_e32 v76, 0x45800000, v0
	v_cndmask_b32_e32 v0, v0, v76, vcc
	global_load_dwordx4 v[76:79], v[64:65], off
	global_load_dwordx4 v[80:83], v35, s[42:43]
	global_load_dwordx4 v[84:87], v35, s[40:41]
	v_pk_mul_f32 v[12:13], v[12:13], v[0:1] op_sel_hi:[1,0]
	v_pk_mul_f32 v[10:11], v[10:11], v[0:1] op_sel_hi:[1,0]
	v_pk_mul_f32 v[18:19], v[18:19], v[0:1] op_sel_hi:[1,0]
	v_pk_mul_f32 v[22:23], v[22:23], v[0:1] op_sel_hi:[1,0]
	v_pk_mul_f32 v[30:31], v[30:31], v[0:1] op_sel_hi:[1,0]
	v_pk_mul_f32 v[26:27], v[26:27], v[0:1] op_sel_hi:[1,0]
	v_pk_mul_f32 v[14:15], v[14:15], v[0:1] op_sel_hi:[1,0]
	v_pk_mul_f32 v[8:9], v[8:9], v[0:1] op_sel_hi:[1,0]
	v_pk_mul_f32 v[6:7], v[6:7], v[0:1] op_sel_hi:[1,0]
	v_pk_mul_f32 v[4:5], v[4:5], v[0:1] op_sel_hi:[1,0]
	v_pk_mul_f32 v[2:3], v[2:3], v[0:1] op_sel_hi:[1,0]
	s_waitcnt vmcnt(2)
	v_pk_mul_f32 v[10:11], v[76:77], v[10:11]
	v_pk_mul_f32 v[12:13], v[78:79], v[12:13]
	s_waitcnt vmcnt(0)
	v_pk_add_f32 v[76:77], v[86:87], 1.0 op_sel_hi:[1,0]
	v_pk_add_f32 v[78:79], v[84:85], 1.0 op_sel_hi:[1,0]
	v_pk_fma_f32 v[12:13], v[76:77], v[12:13], v[82:83]
	v_pk_fma_f32 v[10:11], v[78:79], v[10:11], v[80:81]
	s_nop 0
	v_cvt_pk_bf16_f32 v10, v10, v11
	v_cvt_pk_bf16_f32 v11, v12, v13
	v_lshl_add_u64 v[12:13], v[74:75], 0, s[10:11]
	global_store_dwordx2 v[12:13], v[10:11], off
	global_load_dwordx4 v[76:79], v[64:65], off offset:1024
	global_load_dwordx4 v[80:83], v35, s[42:43] offset:1024
	global_load_dwordx4 v[84:87], v43, s[40:41]
	v_pk_mul_f32 v[10:11], v[20:21], v[0:1] op_sel_hi:[1,0]
	s_waitcnt vmcnt(2)
	v_pk_mul_f32 v[18:19], v[76:77], v[18:19]
	v_pk_mul_f32 v[10:11], v[78:79], v[10:11]
	s_waitcnt vmcnt(0)
	v_pk_add_f32 v[20:21], v[86:87], 1.0 op_sel_hi:[1,0]
	v_pk_add_f32 v[76:77], v[84:85], 1.0 op_sel_hi:[1,0]
	v_pk_fma_f32 v[10:11], v[20:21], v[10:11], v[82:83]
	v_pk_fma_f32 v[18:19], v[76:77], v[18:19], v[80:81]
	s_nop 0
	v_cvt_pk_bf16_f32 v18, v18, v19
	v_cvt_pk_bf16_f32 v19, v10, v11
	global_store_dwordx2 v[12:13], v[18:19], off offset:512
	global_load_dwordx4 v[18:21], v[64:65], off offset:2048
	s_nop 0
	global_load_dwordx4 v[76:79], v35, s[42:43] offset:2048
	global_load_dwordx4 v[80:83], v45, s[40:41]
	v_pk_mul_f32 v[10:11], v[24:25], v[0:1] op_sel_hi:[1,0]
	s_waitcnt vmcnt(2)
	v_pk_mul_f32 v[18:19], v[18:19], v[22:23]
	v_pk_mul_f32 v[10:11], v[20:21], v[10:11]
	s_waitcnt vmcnt(0)
	v_pk_add_f32 v[20:21], v[82:83], 1.0 op_sel_hi:[1,0]
	v_pk_add_f32 v[22:23], v[80:81], 1.0 op_sel_hi:[1,0]
	v_pk_fma_f32 v[10:11], v[20:21], v[10:11], v[78:79]
	v_pk_fma_f32 v[18:19], v[22:23], v[18:19], v[76:77]
	s_nop 0
	v_cvt_pk_bf16_f32 v18, v18, v19
	v_cvt_pk_bf16_f32 v19, v10, v11
	global_store_dwordx2 v[12:13], v[18:19], off offset:1024
	global_load_dwordx4 v[18:21], v[64:65], off offset:3072
	s_nop 0
	global_load_dwordx4 v[22:25], v35, s[42:43] offset:3072
	global_load_dwordx4 v[76:79], v47, s[40:41]
	v_pk_mul_f32 v[10:11], v[32:33], v[0:1] op_sel_hi:[1,0]
	s_waitcnt vmcnt(2)
	v_pk_mul_f32 v[18:19], v[30:31], v[18:19]
	v_pk_mul_f32 v[10:11], v[10:11], v[20:21]
	s_waitcnt vmcnt(0)
	v_pk_add_f32 v[20:21], v[78:79], 1.0 op_sel_hi:[1,0]
	v_pk_add_f32 v[30:31], v[76:77], 1.0 op_sel_hi:[1,0]
	v_pk_fma_f32 v[10:11], v[10:11], v[20:21], v[24:25]
	v_pk_fma_f32 v[18:19], v[18:19], v[30:31], v[22:23]
	s_nop 0
	v_cvt_pk_bf16_f32 v18, v18, v19
	v_cvt_pk_bf16_f32 v19, v10, v11
	global_store_dwordx2 v[12:13], v[18:19], off offset:1536
	global_load_dwordx4 v[18:21], v[66:67], off
	s_nop 0
	global_load_dwordx4 v[22:25], v49, s[42:43]
	global_load_dwordx4 v[30:33], v49, s[40:41]
	v_pk_mul_f32 v[10:11], v[28:29], v[0:1] op_sel_hi:[1,0]
	s_waitcnt vmcnt(2)
	v_pk_mul_f32 v[18:19], v[26:27], v[18:19]
	v_pk_mul_f32 v[10:11], v[10:11], v[20:21]
	s_waitcnt vmcnt(0)
	v_pk_add_f32 v[20:21], v[32:33], 1.0 op_sel_hi:[1,0]
	v_pk_add_f32 v[26:27], v[30:31], 1.0 op_sel_hi:[1,0]
	v_pk_fma_f32 v[10:11], v[10:11], v[20:21], v[24:25]
	v_pk_fma_f32 v[18:19], v[18:19], v[26:27], v[22:23]
	s_nop 0
	v_cvt_pk_bf16_f32 v18, v18, v19
	v_cvt_pk_bf16_f32 v19, v10, v11
	global_store_dwordx2 v[12:13], v[18:19], off offset:2048
	global_load_dwordx4 v[18:21], v[68:69], off
	s_nop 0
	global_load_dwordx4 v[22:25], v53, s[42:43]
	global_load_dwordx4 v[26:29], v53, s[40:41]
	v_pk_mul_f32 v[10:11], v[16:17], v[0:1] op_sel_hi:[1,0]
	s_waitcnt vmcnt(2)
	v_pk_mul_f32 v[14:15], v[14:15], v[18:19]
	v_pk_mul_f32 v[10:11], v[10:11], v[20:21]
	s_waitcnt vmcnt(0)
	v_pk_add_f32 v[16:17], v[28:29], 1.0 op_sel_hi:[1,0]
	v_pk_add_f32 v[18:19], v[26:27], 1.0 op_sel_hi:[1,0]
	v_pk_fma_f32 v[10:11], v[10:11], v[16:17], v[24:25]
	v_pk_fma_f32 v[14:15], v[14:15], v[18:19], v[22:23]
	s_nop 0
	v_cvt_pk_bf16_f32 v14, v14, v15
	v_cvt_pk_bf16_f32 v15, v10, v11
	global_store_dwordx2 v[12:13], v[14:15], off offset:2560
	global_load_dwordx4 v[14:17], v[70:71], off
	s_nop 0
	global_load_dwordx4 v[18:21], v57, s[42:43]
	global_load_dwordx4 v[22:25], v57, s[40:41]
	s_waitcnt vmcnt(2)
	v_pk_mul_f32 v[6:7], v[6:7], v[14:15]
	v_pk_mul_f32 v[8:9], v[8:9], v[16:17]
	s_waitcnt vmcnt(0)
	v_pk_add_f32 v[10:11], v[24:25], 1.0 op_sel_hi:[1,0]
	v_pk_add_f32 v[14:15], v[22:23], 1.0 op_sel_hi:[1,0]
	v_pk_fma_f32 v[8:9], v[8:9], v[10:11], v[20:21]
	v_pk_fma_f32 v[6:7], v[6:7], v[14:15], v[18:19]
	s_nop 0
	v_cvt_pk_bf16_f32 v6, v6, v7
	v_cvt_pk_bf16_f32 v7, v8, v9
	global_store_dwordx2 v[12:13], v[6:7], off offset:3072
	global_load_dwordx4 v[6:9], v[72:73], off
	s_nop 0
	global_load_dwordx4 v[14:17], v61, s[42:43]
	global_load_dwordx4 v[18:21], v61, s[40:41]
	s_waitcnt vmcnt(2)
	v_pk_mul_f32 v[2:3], v[2:3], v[6:7]
	v_pk_mul_f32 v[4:5], v[4:5], v[8:9]
	s_waitcnt vmcnt(0)
	v_pk_add_f32 v[6:7], v[20:21], 1.0 op_sel_hi:[1,0]
	v_pk_add_f32 v[8:9], v[18:19], 1.0 op_sel_hi:[1,0]
	v_pk_fma_f32 v[4:5], v[4:5], v[6:7], v[16:17]
	v_pk_fma_f32 v[2:3], v[2:3], v[8:9], v[14:15]
	s_nop 0
	v_cvt_pk_bf16_f32 v2, v2, v3
	v_cvt_pk_bf16_f32 v3, v4, v5
	global_store_dwordx2 v[12:13], v[2:3], off offset:3584
	s_branch .LBB0_1104
